# producer per-channel constants hoisted out of the scan loop into registers; NA split 1792 (rebalance phase 1 vs phase 2)
# baseline (speedup 1.0000x reference)
; __device__ __forceinline__ void na_phase(const Params& p, int l, unsigned char* shm, int item_lo, int item_hi, int wg, int nwg) {
;     ...
;     for (int item = item_lo + wg; item < item_hi; item += nwg) {
;         const int h = item & 7, i = (item >> 3) & 255, b = item >> 11;
;         const int s0 = min(max(i - 4, 0), 248);
;         bf16x8 qf[4][2];
; #pragma unroll
;         for (int mt = 0; mt < 4; ++mt)
; #pragma unroll
;             for (int ks = 0; ks < 2; ++ks) qf[mt][ks] = *(const bf16x8*)(Z + (size_t)(b * T + i * 64 + 16 * mt + n_) * ZLD + ZC_NAQ + h * 64 + 32 * ks + 8 * kg);
; #pragma unroll
;         for (int it = 0; it < 8; ++it) { const int idx = it * NTHR + tid, key = idx >> 3, ch = idx & 7;
;             const size_t tok = (size_t)b * T + (size_t)(s0 + (key >> 6)) * 64 + (key & 63);
;             *(u32x4*)(Ks + key * 144 + ch * 16) = *(const u32x4*)(Z + tok * ZLD + ZC_NAK + h * 64 + ch * 8); }
;         { const size_t tok = (size_t)b * T + (size_t)(s0 + (tid >> 6)) * 64 + (tid & 63);
; #pragma unroll
;           for (int it = 0; it < 8; ++it) { const u32x4 v4 = *(const u32x4*)(Z + tok * ZLD + ZC_NAV + h * 64 + it * 8); const unsigned vv[4] = {v4.x, v4.y, v4.z, v4.w};
; #pragma unroll
;               for (int e = 0; e < 4; ++e) { *(bf16_t*)(Vt + (it * 8 + 2 * e) * 1040 + tid * 2) = (bf16_t)(vv[e] & 0xffffu); *(bf16_t*)(Vt + (it * 8 + 2 * e + 1) * 1040 + tid * 2) = (bf16_t)(vv[e] >> 16); } } }
;         if (lane < 31) brow[w * 32 + lane] = rpb[(size_t)h * 15 * 31 + (size_t)(s0 + w - i + 7) * 31 + lane];
; __global__ void __launch_bounds__(NTHR, 2) mega(Params p) {
;     ...
;                        ret_output(p, shm, wg, nwg); __syncthreads(); convert_rest(p, l, shm, wg, nwg); __syncthreads(); na_phase(p, l, shm, NA_SPLIT, BATCH * 256 * 8, wg, nwg); } break;
.LBB0_146:
	v_writelane_b32 v254, s46, 63
	v_mov_b32_e32 v5, v160
	s_cmpk_gt_i32 s8, 0x9bf
	v_writelane_b32 v252, s47, 0
	s_barrier
	s_cbranch_scc1 .LBB0_295
	v_readlane_b32 s0, v254, 63
	v_readlane_b32 s1, v252, 0
	s_mov_b32 s2, s0
	v_readlane_b32 s36, v254, 9
	s_mul_i32 s1, s2, 0x3a20
	v_readlane_b32 s42, v254, 15
	v_ashrrev_i32_e32 v47, 6, v5
	v_and_b32_e32 v2, 48, v5
	v_mov_b32_e32 v3, v1
	v_and_b32_e32 v0, 7, v5
	s_mul_hi_i32 s0, s0, 0x3a20
	v_readlane_b32 s43, v254, 16
	s_add_u32 s2, s42, s1
	v_bfe_u32 v8, v5, 4, 2
	v_lshl_add_u64 v[48:49], s[78:79], 0, v[2:3]
	s_waitcnt vmcnt(4)
	v_lshlrev_b32_e32 v6, 3, v0
	v_lshl_add_u32 v3, v0, 4, 0
	v_and_b32_e32 v0, 3, v47
	s_addc_u32 s3, s43, s0
	v_and_b32_e32 v53, 15, v5
	s_add_i32 s23, s8, 0x640
	v_lshlrev_b32_e32 v12, 2, v8
	v_cmp_ne_u32_e64 s[6:7], 0, v0
	v_cmp_ne_u32_e64 s[8:9], 3, v0
	v_lshlrev_b32_e32 v0, 4, v0
	v_or_b32_e32 v4, v0, v53
	v_or_b32_e32 v57, v0, v12
	v_lshlrev_b32_e32 v0, 1, v53
	v_lshl_add_u64 v[50:51], s[78:79], 0, v[0:1]
	v_add_u32_e32 v0, 0x200, v5
	v_ashrrev_i32_e32 v19, 3, v0
	v_ashrrev_i32_e32 v61, 9, v0
	v_add_u32_e32 v0, 0x400, v5
	v_ashrrev_i32_e32 v20, 3, v0
	v_ashrrev_i32_e32 v63, 9, v0
	v_add_u32_e32 v0, 0x600, v5
	v_ashrrev_i32_e32 v21, 3, v0
	v_ashrrev_i32_e32 v65, 9, v0
	v_add_u32_e32 v0, 0x800, v5
	v_ashrrev_i32_e32 v22, 3, v0
	v_ashrrev_i32_e32 v67, 9, v0
	v_add_u32_e32 v0, 0xa00, v5
	v_ashrrev_i32_e32 v23, 3, v0
	v_ashrrev_i32_e32 v70, 9, v0
	v_add_u32_e32 v0, 0xc00, v5
	v_writelane_b32 v252, s2, 1
	v_and_b32_e32 v46, 63, v5
	v_readlane_b32 s0, v253, 42
	v_lshlrev_b32_e32 v9, 7, v47
	v_ashrrev_i32_e32 v24, 3, v0
	v_ashrrev_i32_e32 v71, 9, v0
	v_add_u32_e32 v0, 0xe00, v5
	v_writelane_b32 v252, s3, 2
	v_lshl_add_u32 v7, v46, 2, s0
	v_lshlrev_b32_e32 v55, 1, v5
	v_cmp_gt_u32_e64 s[2:3], 31, v46
	v_and_b32_e32 v10, 0xfffffcf, v5
	v_add_u32_e32 v13, s0, v9
	v_and_b32_e32 v14, 0xffffffc0, v5
	s_movk_i32 s26, 0x410
	v_ashrrev_i32_e32 v17, 3, v5
	v_ashrrev_i32_e32 v59, 9, v5
	s_movk_i32 s0, 0x90
	v_ashrrev_i32_e32 v25, 3, v0
	v_ashrrev_i32_e32 v72, 9, v0
	v_or_b32_e32 v0, 48, v5
	v_sub_u32_e64 v5, v12, 8 clamp
	v_readlane_b32 s37, v254, 10
	v_readlane_b32 s38, v254, 11
	v_readlane_b32 s39, v254, 12
	v_readlane_b32 s40, v254, 13
	v_readlane_b32 s41, v254, 14
	v_readlane_b32 s44, v254, 17
	v_readlane_b32 s45, v254, 18
	v_readlane_b32 s46, v254, 19
	v_readlane_b32 s47, v254, 20
	v_readlane_b32 s48, v254, 21
	v_readlane_b32 s49, v254, 22
	v_readlane_b32 s50, v254, 23
	v_readlane_b32 s51, v254, 24
	v_writelane_b32 v254, s2, 41
	v_mad_u32_u24 v16, v4, s26, 0
	v_and_b32_e32 v4, 0xffffffe0, v17
	v_and_b32_e32 v52, 63, v17
	v_mul_lo_u32 v17, v17, s0
	v_and_b32_e32 v54, 63, v19
	v_mul_lo_u32 v19, v19, s0
	v_and_b32_e32 v56, 63, v20
	v_mul_lo_u32 v20, v20, s0
	v_and_b32_e32 v58, 63, v21
	v_mul_lo_u32 v21, v21, s0
	v_and_b32_e32 v60, 63, v22
	v_mul_lo_u32 v22, v22, s0
	v_and_b32_e32 v62, 63, v23
	v_mul_lo_u32 v23, v23, s0
	v_and_b32_e32 v64, 63, v24
	v_mul_lo_u32 v24, v24, s0
	v_and_b32_e32 v66, 63, v25
	v_mul_lo_u32 v25, v25, s0
	v_mul_lo_u32 v10, v10, s0
	v_mul_lo_u32 v26, v0, s0
	v_cmp_ge_u32_e64 s[0:1], v53, v5
	v_sub_u32_e32 v5, v53, v12
	v_writelane_b32 v254, s3, 42
	v_lshl_add_u32 v74, v5, 2, v13
	v_or_b32_e32 v5, 1, v12
	v_writelane_b32 v254, s0, 43
	v_sub_u32_e64 v27, v5, 8 clamp
	v_mul_u32_u24_e32 v75, 0x1040, v8
	v_writelane_b32 v254, s1, 44
	v_max_u32_e32 v8, 8, v5
	v_cmp_ge_u32_e64 s[0:1], v53, v27
	v_sub_u32_e32 v27, v53, v5
	v_mul_u32_u24_e32 v77, 0x410, v5
	v_or_b32_e32 v5, 2, v12
	v_writelane_b32 v254, s0, 45
	v_lshl_add_u32 v76, v27, 2, v13
	v_max_u32_e32 v27, 8, v5
	v_sub_u32_e64 v28, v5, 8 clamp
	v_sub_u32_e32 v5, v53, v5
	v_writelane_b32 v254, s1, 46
	v_cmp_ge_u32_e64 s[0:1], v53, v28
	v_lshl_add_u32 v78, v5, 2, v13
	v_or_b32_e32 v5, 3, v12
	v_and_b32_e32 v0, 0xffffff9e, v55
	v_writelane_b32 v254, s0, 47
	v_sub_u32_e64 v29, v5, 8 clamp
	v_add_u32_e32 v73, 0, v0
	v_max_u32_e32 v0, 8, v12
	v_writelane_b32 v254, s1, 48
	v_max_u32_e32 v28, 8, v5
	v_cmp_ge_u32_e64 s[0:1], v53, v29
	v_sub_u32_e32 v5, v53, v5
	v_add_u32_e32 v0, 8, v0
	v_writelane_b32 v254, s0, 49
	v_lshl_add_u32 v79, v5, 2, v13
	v_or_b32_e32 v5, 16, v53
	v_writelane_b32 v254, s1, 50
	v_cmp_lt_u32_e64 s[0:1], v5, v0
	v_add_u32_e32 v8, 8, v8
	v_add_u32_e32 v27, 8, v27
	v_writelane_b32 v254, s0, 51
	v_add_u32_e32 v28, 8, v28
	v_readlane_b32 s25, v253, 43
	v_writelane_b32 v254, s1, 52
	v_cmp_lt_u32_e64 s[0:1], v5, v8
	v_or_b32_e32 v8, 32, v53
	v_or_b32_e32 v0, v8, v14
	v_writelane_b32 v254, s0, 53
	v_lshl_add_u32 v81, v0, 1, 0
	v_lshl_add_u32 v15, v14, 2, s25
	v_writelane_b32 v254, s1, 54
	v_cmp_lt_u32_e64 s[0:1], v5, v27
	v_or_b32_e32 v27, 48, v53
	v_or_b32_e32 v0, v27, v14
	v_writelane_b32 v254, s0, 55
	v_or_b32_e32 v29, v5, v14
	v_lshl_add_u32 v82, v0, 1, 0
	v_writelane_b32 v254, s1, 56
	v_cmp_lt_u32_e64 s[0:1], v5, v28
	v_or_b32_e32 v0, 16, v12
	v_add_u32_e32 v14, 8, v12
	v_writelane_b32 v254, s0, 57
	v_lshl_add_u32 v80, v29, 1, 0
	v_sub_u32_e32 v29, v53, v0
	v_writelane_b32 v254, s1, 58
	v_cmp_ge_u32_e64 s[0:1], v53, v14
	v_mul_u32_u24_e32 v84, 0x410, v0
	v_or_b32_e32 v0, 17, v12
	v_writelane_b32 v254, s0, 59
	v_lshl_add_u32 v83, v29, 2, v13
; __device__ __forceinline__ float bf2f(bf16_t b) { return __uint_as_float(((unsigned)b) << 16); }
; __device__ __forceinline__ bf16_t f2bf(float f) { return (bf16_t)(cvt_pk_bf16(f, 0.f) & 0xffffu); }
; __device__ __forceinline__ float allreduce16(float x) { x += dppf(x, 0); x += dppf(x, 1); x += dppf(x, 2); x += dppf(x, 3); return x; }
; __device__ __forceinline__ void na_phase(const Params& p, int l, unsigned char* shm, int item_lo, int item_hi, int wg, int nwg) {
;     ...
;         for (int mt = 0; mt < 4; ++mt) {
;             float rs[4] = {0.f, 0.f, 0.f, 0.f};
; #pragma unroll
;             for (int nt = 0; nt < 4; ++nt)
; #pragma unroll
;                 for (int i2 = 0; i2 < 4; ++i2) { const int q = 16 * mt + 4 * kg + i2, col = 16 * nt + n_, cs = min(max(q - 8, 0), 48); const bool ok = (col >= cs) && (col < cs + 16);
;                     const float s = acc[mt][nt][i2] * 0.125f + brow[w * 32 + (ok ? col - q + 15 : 0)];
;                     const bf16_t pb = f2bf(ok ? __expf(fminf(s, 60.0f)) : 0.0f);
;                     rs[i2] += bf2f(pb);
;                     *(bf16_t*)(Ks + q * 1040 + (w * 64 + col) * 2) = pb; }
; #pragma unroll
;             for (int i2 = 0; i2 < 4; ++i2) { const float t_ = allreduce16(rs[i2]); if (n_ == 0) red[w * 64 + 16 * mt + 4 * kg + i2] = t_; }
	v_add_u32_e32 v29, 9, v12
	v_sub_u32_e32 v0, v53, v0
	v_writelane_b32 v254, s1, 60
	v_cmp_ge_u32_e64 s[0:1], v53, v29
	v_lshl_add_u32 v85, v0, 2, v13
	v_or_b32_e32 v0, 18, v12
	v_writelane_b32 v254, s0, 61
	v_add_u32_e32 v31, 10, v12
	v_sub_u32_e32 v0, v53, v0
	v_writelane_b32 v254, s1, 62
	v_cmp_ge_u32_e64 s[0:1], v53, v31
	v_lshl_add_u32 v86, v0, 2, v13
	v_or_b32_e32 v0, 19, v12
	v_add_u32_e32 v28, 24, v12
	v_writelane_b32 v254, s0, 39
	v_sub_u32_e32 v0, v53, v0
	v_add_u32_e32 v30, 25, v12
	v_writelane_b32 v254, s1, 40
	v_lshl_add_u32 v87, v0, 2, v13
	v_cmp_ge_u32_e32 vcc, v5, v14
	v_cmp_lt_u32_e64 s[0:1], v5, v28
	v_or_b32_e32 v0, 32, v12
	v_add_u32_e32 v32, 26, v12
	s_and_b64 s[2:3], vcc, s[0:1]
	v_cmp_ge_u32_e32 vcc, v5, v29
	v_cmp_lt_u32_e64 s[0:1], v5, v30
	v_mul_u32_u24_e32 v88, 0x410, v0
	v_or_b32_e32 v14, 33, v12
	v_sub_u32_e32 v0, v53, v0
	v_add_u32_e32 v33, 11, v12
	v_add_u32_e32 v34, 27, v12
	s_and_b64 s[10:11], vcc, s[0:1]
	v_cmp_ge_u32_e32 vcc, v5, v31
	v_cmp_lt_u32_e64 s[0:1], v5, v32
	v_or_b32_e32 v31, 34, v12
	v_lshl_add_u32 v89, v0, 2, v13
	v_sub_u32_e32 v0, v53, v14
	v_cmp_ge_u32_e64 s[36:37], v5, v28
	v_cmp_ge_u32_e64 s[38:39], v5, v30
	v_cmp_ge_u32_e64 s[40:41], v5, v32
	s_and_b64 s[12:13], vcc, s[0:1]
	v_cmp_ge_u32_e32 vcc, v5, v33
	v_cmp_ge_u32_e64 s[42:43], v5, v34
	v_cmp_lt_u32_e64 s[0:1], v5, v34
	v_add_u32_e32 v5, 40, v12
	v_or_b32_e32 v35, 35, v12
	v_lshl_add_u32 v90, v0, 2, v13
	v_sub_u32_e32 v0, v53, v31
	s_and_b64 s[14:15], vcc, s[0:1]
	v_add_u32_e32 v29, 41, v12
	v_lshl_add_u32 v91, v0, 2, v13
	v_sub_u32_e32 v0, v53, v35
	v_cmp_ge_u32_e32 vcc, v8, v28
	v_cmp_lt_u32_e64 s[0:1], v8, v5
	v_cmp_ge_u32_e64 s[34:35], v53, v33
	v_add_u32_e32 v33, 42, v12
	v_lshl_add_u32 v92, v0, 2, v13
	s_and_b64 s[16:17], vcc, s[0:1]
	v_cmp_ge_u32_e32 vcc, v8, v30
	v_cmp_lt_u32_e64 s[0:1], v8, v29
	v_cmp_lt_u32_e64 s[30:31], v27, v5
	v_or_b32_e32 v0, 48, v12
	v_min_u32_e32 v5, 8, v12
	v_cmp_lt_u32_e64 s[46:47], v8, v30
	s_and_b64 s[18:19], vcc, s[0:1]
	v_cmp_ge_u32_e32 vcc, v8, v32
	v_cmp_lt_u32_e64 s[0:1], v8, v33
	v_cmp_lt_u32_e64 s[54:55], v27, v29
	v_add_u32_e32 v29, 40, v5
	v_add_u32_e32 v30, 56, v5
	v_mul_u32_u24_e32 v93, 0x410, v0
	v_or_b32_e32 v5, 49, v12
	v_sub_u32_e32 v0, v53, v0
	v_cmp_lt_u32_e64 s[50:51], v8, v34
	s_and_b64 s[20:21], vcc, s[0:1]
	v_cmp_ge_u32_e32 vcc, v8, v34
	v_or_b32_e32 v34, 50, v12
	v_lshl_add_u32 v94, v0, 2, v13
	v_sub_u32_e32 v0, v53, v5
	v_or_b32_e32 v18, v4, v53
	v_or_b32_e32 v38, 51, v12
	v_lshl_add_u32 v95, v0, 2, v13
	v_sub_u32_e32 v0, v53, v34
	v_add_u32_e32 v36, 43, v12
	s_add_i32 s24, 0, 0x12000
	v_mul_lo_u32 v18, v18, s26
	v_min_u32_e32 v31, 7, v12
	v_min_u32_e32 v35, 6, v12
	v_min_u32_e32 v12, 5, v12
	v_lshl_add_u32 v96, v0, 2, v13
	v_sub_u32_e32 v0, v53, v38
	v_add_u32_e32 v11, 0, v2
	v_cmp_lt_u32_e64 s[44:45], v8, v28
	v_cmp_lt_u32_e64 s[48:49], v8, v32
	v_cmp_lt_u32_e64 s[0:1], v8, v36
	v_add_u32_e32 v14, s24, v2
	v_add_u32_e32 v28, s24, v18
	v_add_u32_e32 v32, 41, v31
	v_add_u32_e32 v31, 57, v31
	v_add_u32_e32 v37, 42, v35
	v_add_u32_e32 v35, 58, v35
	v_add_u32_e32 v39, 43, v12
	v_add_u32_e32 v12, 59, v12
	v_lshl_add_u32 v97, v0, 2, v13
	v_or_b32_e32 v13, 64, v2
	v_or_b32_e32 v34, 0x80, v2
	v_or_b32_e32 v38, 0xc0, v2
	v_or_b32_e32 v40, 0x100, v2
	v_or_b32_e32 v41, 0x140, v2
	v_or_b32_e32 v42, 0x180, v2
	v_or_b32_e32 v43, 0x1c0, v2
	v_or_b32_e32 v44, 0x200, v2
	v_or_b32_e32 v45, 0x240, v2
	v_or_b32_e32 v68, 0x280, v2
	v_or_b32_e32 v69, 0x2c0, v2
	v_or_b32_e32 v128, 0x300, v2
	v_or_b32_e32 v129, 0x340, v2
	v_or_b32_e32 v142, 0x380, v2
	v_or_b32_e32 v143, 0x3c0, v2
	v_ashrrev_i32_e32 v5, 31, v4
	v_or_b32_e32 v99, 1, v57
	v_or_b32_e32 v101, 2, v57
	v_or_b32_e32 v103, 3, v57
	v_cmp_eq_u32_e64 s[4:5], 0, v53
	s_and_b64 s[0:1], vcc, s[0:1]
	v_lshl_add_u32 v98, v57, 2, s25
	v_lshl_add_u32 v100, v99, 2, s25
	v_lshl_add_u32 v102, v101, 2, s25
	v_lshl_add_u32 v104, v103, 2, s25
	v_lshlrev_b32_e32 v0, 1, v6
	v_add_u32_e32 v105, v3, v17
	v_add_u32_e32 v106, v3, v19
	v_add_u32_e32 v107, v3, v20
	v_add_u32_e32 v108, v3, v21
	v_add_u32_e32 v109, v3, v22
	v_add_u32_e32 v110, v3, v23
	v_add_u32_e32 v111, v3, v24
	v_add_u32_e32 v112, v3, v25
	v_add_u32_e32 v113, v7, v9
	v_add_u32_e32 v114, v11, v10
	v_add_u32_e32 v115, v11, v26
	v_add_u32_e32 v116, v14, v18
	v_add_u32_e32 v117, v28, v13
	v_add_u32_e32 v118, v28, v34
	v_add_u32_e32 v119, v28, v38
	v_add_u32_e32 v120, v28, v40
	v_add_u32_e32 v121, v28, v41
	v_add_u32_e32 v122, v28, v42
	v_add_u32_e32 v123, v28, v43
	v_add_u32_e32 v124, v28, v44
	v_add_u32_e32 v125, v28, v45
	v_add_u32_e32 v126, v28, v68
	v_add_u32_e32 v127, v28, v69
	v_add_u32_e32 v128, v28, v128
	v_add_u32_e32 v129, v28, v129
	v_add_u32_e32 v142, v28, v142
	v_add_u32_e32 v143, v28, v143
	v_lshlrev_b64 v[68:69], 1, v[4:5]
	v_add_u32_e32 v144, v15, v2
	v_add_u32_e32 v145, v16, v2
	v_cmp_lt_u32_e64 s[56:57], v27, v33
	v_cmp_lt_u32_e64 s[58:59], v27, v36
	v_cmp_ge_u32_e64 s[60:61], v8, v29
	v_cmp_ge_u32_e64 s[62:63], v8, v32
	v_cmp_ge_u32_e64 s[64:65], v8, v37
	v_cmp_ge_u32_e64 s[66:67], v8, v39
	v_cmp_lt_u32_e64 s[68:69], v27, v30
	v_cmp_lt_u32_e64 s[70:71], v27, v31
	v_cmp_lt_u32_e64 s[72:73], v27, v35
	v_cmp_lt_u32_e64 s[74:75], v27, v12
	s_branch .LBB0_149

; __device__ __forceinline__ float sigmoidf_(float x) { return __builtin_amdgcn_rcpf(1.0f + __expf(-x)); }
; #define RW_ISSUE(CK) do { const int st_ = (CK) * TC + ptok; const int t_ = d ? (T - 1 - st_) : st_; const bf16_t* zr_ = rw_row(p.ws, b * T + t_); \
;             _Pragma("unroll") for (int g = 0; g < 5; ++g) rc[g] = *(const u32x4*)(zr_ + offs[g]); } while (0)
; __device__ void rw_scan(const Params& p, int l, unsigned char* shm, int item) {
;     ...
;     if (w >= 4) {
;         const int pw = w - 4, ptok = pw * 8 + (lane >> 3), sub = lane & 7;
;         const int r_ = lane & 15, kg = lane >> 4;
;         bf16x8 bfr[2][4][2];
; #pragma unroll
;         for (int mtx = 0; mtx < 2; ++mtx)
; #pragma unroll
;             for (int nt = 0; nt < 4; ++nt)
; #pragma unroll
;                 for (int ks2 = 0; ks2 < 2; ++ks2) bfr[mtx][nt][ks2] = *(const bf16x8*)(bfl + ((size_t)((mtx * 4 + nt) * 2 + ks2) * 64 + lane) * 16);
;         const int offs[5] = {h * 64 + sub * 8, 768 + h * 64 + sub * 8, 1536 + h * 64 + sub * 8, 2304 + d * 64 + sub * 8, 2432 + d * 64 + sub * 8};
;         u32x4 rc[5];
;         float* wl = wla + pw * 1024; float* al = wl + 512;
;     ...
;         RW_ISSUE(0);
;     ...
;                 for (int e = 0; e < 8; ++e) { const float wa = cst[sub * 8 + e] + (e < 4 ? wl0[e & 3] : wl1[e & 3]), aa = cst[64 + sub * 8 + e] + (e < 4 ? al0[e & 3] : al1[e & 3]);
;                     av[e] = sigmoidf_(aa); dec[e] = __expf(-0.6065306597126334f * sigmoidf_(wa)); kkv[e] = ks_[e] * cst[128 + sub * 8 + e]; ssq += kkv[e] * kkv[e];
;                     kd[e] = ks_[e] * (1.0f + (av[e] - 1.0f) * cst[192 + sub * 8 + e]); bpart += rs_[e] * kd[e] * cst[256 + sub * 8 + e]; }
.LBB0_306:
	s_andn2_saveexec_b64 s[10:11], s[0:1]
	s_cbranch_execz .LBB0_335
	v_add_u32_e32 v75, -4, v4
	v_and_b32_e32 v79, 7, v3
	v_lshrrev_b32_e32 v77, 3, v74
	v_lshlrev_b32_e32 v80, 3, v75
	v_lshlrev_b32_e32 v81, 3, v79
	s_mul_i32 s0, s9, 0x180000
	v_readlane_b32 s1, v253, 18
	v_or_b32_e32 v179, v80, v77
	v_lshl_or_b32 v0, s9, 6, v81
	s_add_u32 s13, s1, s0
	v_readlane_b32 s0, v253, 19
	v_or_b32_e32 v76, 0x900, v0
	v_or_b32_e32 v78, 0x980, v0
	v_sub_u32_e32 v0, 0x3fff, v179
	s_addc_u32 s16, s0, 0
	s_lshl_b32 s0, s8, 6
	v_cndmask_b32_e32 v0, v0, v179, vcc
	s_lshl_b32 s14, s2, 14
	v_or_b32_e32 v126, s0, v81
	s_add_i32 s1, s0, 0x300
	s_addk_i32 s0, 0x600
	v_add_u32_e32 v8, s14, v0
	v_mov_b64_e32 v[6:7], s[94:95]
	v_or_b32_e32 v128, s1, v81
	v_or_b32_e32 v142, s0, v81
	v_mad_i64_i32 v[6:7], s[0:1], v8, s22, v[6:7]
	s_mov_b64 s[0:1], 0xe504c00
	v_and_b32_e32 v0, 0x7f, v0
	v_lshl_add_u64 v[6:7], v[6:7], 0, s[0:1]
	s_movk_i32 s0, 0x7f
	v_cmp_eq_u32_e64 s[0:1], s0, v0
	v_readlane_b32 s2, v253, 20
	v_ashrrev_i32_e32 v8, 6, v8
	v_cndmask_b32_e64 v9, 0, 1, s[0:1]
	v_readlane_b32 s3, v253, 21
	v_and_or_b32 v10, v8, -2, v9
	v_ashrrev_i32_e32 v127, 31, v126
	v_mov_b64_e32 v[8:9], s[2:3]
	s_movk_i32 s2, 0x1500
	v_mad_i64_i32 v[8:9], s[2:3], v10, s2, v[8:9]
	v_cmp_eq_u32_e64 s[2:3], 0, v0
	s_or_b64 s[0:1], s[2:3], s[0:1]
	v_cndmask_b32_e64 v7, v7, v9, s[0:1]
	v_cndmask_b32_e64 v6, v6, v8, s[0:1]
	v_mov_b32_e32 v129, v1
	v_lshl_add_u64 v[8:9], v[126:127], 1, v[6:7]
	v_lshl_add_u64 v[10:11], v[128:129], 1, v[6:7]
	v_lshlrev_b32_e32 v0, 1, v76
	global_load_dwordx4 v[90:93], v[8:9], off
	global_load_dwordx4 v[98:101], v[10:11], off
	v_mov_b32_e32 v143, v1
	v_lshl_add_u64 v[10:11], v[6:7], 0, v[0:1]
	v_lshlrev_b32_e32 v0, 1, v78
	v_lshl_add_u64 v[8:9], v[142:143], 1, v[6:7]
	v_lshl_add_u64 v[6:7], v[6:7], 0, v[0:1]
	global_load_dwordx4 v[70:73], v[8:9], off
	global_load_dwordx4 v[86:89], v[10:11], off
	global_load_dwordx4 v[82:85], v[6:7], off
	v_lshlrev_b32_e32 v0, 4, v74
	v_add_u32_e32 v6, 0, v0
	v_add_u32_e32 v14, 0x17000, v6
	ds_read_b128 v[62:65], v14
	ds_read_b128 v[58:61], v14 offset:1024
	ds_read_b128 v[42:45], v14 offset:2048
	ds_read_b128 v[38:41], v14 offset:3072
	ds_read_b128 v[26:29], v14 offset:4096
	ds_read_b128 v[22:25], v14 offset:5120
	ds_read_b128 v[10:13], v14 offset:6144
	ds_read_b128 v[6:9], v14 offset:7168
	ds_read_b128 v[66:69], v14 offset:8192
	ds_read_b128 v[54:57], v14 offset:9216
	ds_read_b128 v[50:53], v14 offset:10240
	ds_read_b128 v[46:49], v14 offset:11264
	ds_read_b128 v[34:37], v14 offset:12288
	ds_read_b128 v[30:33], v14 offset:13312
	ds_read_b128 v[18:21], v14 offset:14336
	ds_read_b128 v[14:17], v14 offset:15360
	v_readlane_b32 s0, v253, 46
	v_add_lshl_u32 v80, v80, v2, 7
	v_lshlrev_b32_e32 v95, 7, v179
	v_lshl_add_u32 v75, v75, 12, s0
	v_readlane_b32 s0, v253, 47
	v_and_b32_e32 v80, 0xf80, v80
	v_lshlrev_b32_e32 v94, 5, v79
	v_add_u32_e32 v96, s0, v95
	v_add_u32_e32 v102, s0, v80
	s_movk_i32 s0, 0x100
	v_and_or_b32 v0, v0, s0, v2
	v_lshlrev_b32_e32 v2, 8, v77
	v_readlane_b32 s1, v253, 48
	v_add3_u32 v184, v75, v94, v2
	s_add_i32 s0, 0, 0x21000
	v_bfe_u32 v2, v3, 1, 2
	s_ashr_i32 s9, s8, 31
	v_add_u32_e32 v95, s1, v95
	v_add_u32_e32 v80, s1, v80
	v_add_u32_e32 v183, s0, v94
	v_cmp_eq_u32_e64 s[4:5], s12, v2
	v_lshlrev_b32_e32 v2, 3, v3
	s_lshl_b64 s[0:1], s[8:9], 2
	v_lshlrev_b32_e32 v97, 4, v79
	v_lshlrev_b32_e32 v180, 6, v179
	v_and_b32_e32 v181, 8, v2
	v_or_b32_e32 v2, s12, v79
	s_add_u32 s12, s13, s0
	v_lshl_or_b32 v190, v4, 3, v77
	s_mov_b32 s15, 0
	v_cmp_gt_u32_e64 s[6:7], 32, v74
	v_or_b32_e32 v182, v180, v81
	v_cmp_eq_u32_e64 s[2:3], 0, v2
	s_addc_u32 s13, s16, s1
	v_lshl_add_u32 v185, v0, 2, v75
	v_sub_u32_e32 v191, 0x3fff, v190
	v_lshlrev_b32_e32 v0, 1, v76
	v_lshlrev_b32_e32 v144, 1, v78
	v_add_u32_e32 v189, v96, v97
	v_add_u32_e32 v188, v95, v97
	v_add_u32_e32 v187, v102, v5
	v_add_u32_e32 v186, v80, v5
	s_mov_b32 s16, 0
	ds_read_b128 v[206:209], v183
	ds_read_b128 v[210:213], v183 offset:16
	ds_read_b128 v[214:217], v183 offset:256
	ds_read_b128 v[218:221], v183 offset:272
	ds_read_b128 v[222:225], v183 offset:512
	ds_read_b128 v[226:229], v183 offset:528
	ds_read_b128 v[230:233], v183 offset:768
	ds_read_b128 v[234:237], v183 offset:784
	ds_read_b128 v[238:241], v183 offset:1024
	ds_read_b128 v[242:245], v183 offset:1040
	s_waitcnt lgkmcnt(0)

; __device__ __forceinline__ float sigmoidf_(float x) { return __builtin_amdgcn_rcpf(1.0f + __expf(-x)); }
; __device__ __forceinline__ float allreduce8(float x) { x += dppf(x, 0); x += dppf(x, 1); x += dppf(x, 2); return x; }
; __device__ void rw_scan(const Params& p, int l, unsigned char* shm, int item) {
;     ...
;                 const int tl = lane >> 3;
;                 const f32x4 wl0 = *(const f32x4*)(wl + tl * 64 + sub * 8), wl1 = *(const f32x4*)(wl + tl * 64 + sub * 8 + 4), al0 = *(const f32x4*)(al + tl * 64 + sub * 8), al1 = *(const f32x4*)(al + tl * 64 + sub * 8 + 4);
;                 float kkv[8], ssq = 0.f, av[8], dec[8], kd[8], bpart = 0.f;
; #pragma unroll
;                 for (int e = 0; e < 8; ++e) { const float wa = cst[sub * 8 + e] + (e < 4 ? wl0[e & 3] : wl1[e & 3]), aa = cst[64 + sub * 8 + e] + (e < 4 ? al0[e & 3] : al1[e & 3]);
;                     av[e] = sigmoidf_(aa); dec[e] = __expf(-0.6065306597126334f * sigmoidf_(wa)); kkv[e] = ks_[e] * cst[128 + sub * 8 + e]; ssq += kkv[e] * kkv[e];
;                     kd[e] = ks_[e] * (1.0f + (av[e] - 1.0f) * cst[192 + sub * 8 + e]); bpart += rs_[e] * kd[e] * cst[256 + sub * 8 + e]; }
;                 ssq = allreduce8(ssq); bpart = allreduce8(bpart);
;                 const float inrm = __builtin_amdgcn_rcpf(fmaxf(__builtin_amdgcn_sqrtf(ssq), 1e-12f));
.LBB0_316:
	s_or_b64 exec, exec, s[0:1]
	v_lshlrev_b32_e32 v146, 16, v98
	v_and_b32_e32 v147, 0xffff0000, v98
	v_lshlrev_b32_e32 v148, 16, v99
	v_and_b32_e32 v149, 0xffff0000, v99
	v_lshlrev_b32_e32 v158, 16, v100
	v_and_b32_e32 v159, 0xffff0000, v100
	v_lshlrev_b32_e32 v156, 16, v101
	v_and_b32_e32 v157, 0xffff0000, v101
	ds_read_b128 v[98:101], v184
	ds_read_b128 v[106:109], v184 offset:16
	ds_read_b128 v[102:105], v184 offset:2048
	ds_read_b128 v[110:113], v184 offset:2064
	v_lshlrev_b32_e32 v94, 16, v90
	s_waitcnt lgkmcnt(0)
	v_add_f32_e32 v102, v102, v214
	v_mul_f32_e32 v102, 0xbfb8aa3b, v102
	v_exp_f32_e32 v102, v102
	v_add_f32_e32 v104, v104, v216
	v_mul_f32_e32 v104, 0xbfb8aa3b, v104
	v_exp_f32_e32 v104, v104
	v_add_f32_e32 v102, 1.0, v102
	v_rcp_f32_e32 v150, v102
	v_add_f32_e32 v102, v103, v215
	v_mul_f32_e32 v102, 0xbfb8aa3b, v102
	v_exp_f32_e32 v102, v102
	v_add_f32_e32 v98, v98, v206
	v_add_f32_e32 v104, 1.0, v104
	v_and_b32_e32 v95, 0xffff0000, v90
	v_add_f32_e32 v102, 1.0, v102
	v_rcp_f32_e32 v151, v102
	v_add_f32_e32 v106, v106, v210
	v_add_f32_e32 v108, v108, v212
	v_lshlrev_b32_e32 v96, 16, v91
	v_pk_add_f32 v[102:103], v[150:151], -1.0 op_sel_hi:[1,0]
	v_add_f32_e32 v107, v107, v211
	s_waitcnt lgkmcnt(2)
	v_pk_fma_f32 v[102:103], v[230:231], v[102:103], 1.0 op_sel_hi:[1,1,0]
	v_and_b32_e32 v97, 0xffff0000, v91
	v_pk_mul_f32 v[102:103], v[102:103], v[146:147]
	v_add_f32_e32 v109, v109, v213
	v_mul_f32_e32 v118, v102, v94
	s_waitcnt lgkmcnt(1)
	v_fma_f32 v145, v238, v118, 0
	v_rcp_f32_e32 v152, v104
	v_add_f32_e32 v104, v105, v217
	v_mul_f32_e32 v104, 0xbfb8aa3b, v104
	v_exp_f32_e32 v104, v104
	v_mul_f32_e32 v118, v103, v95
	v_fmac_f32_e32 v145, v239, v118
	v_add_f32_e32 v104, 1.0, v104
	v_rcp_f32_e32 v153, v104
	v_add_f32_e32 v99, v99, v207
	v_add_f32_e32 v100, v100, v208
	v_add_f32_e32 v101, v101, v209
	v_pk_add_f32 v[104:105], v[152:153], -1.0 op_sel_hi:[1,0]
	v_lshlrev_b32_e32 v90, 16, v92
	v_pk_fma_f32 v[104:105], v[232:233], v[104:105], 1.0 op_sel_hi:[1,1,0]
	s_waitcnt lgkmcnt(1)
	v_add_f32_e32 v110, v110, v218
	v_mul_f32_e32 v110, 0xbfb8aa3b, v110
	v_exp_f32_e32 v110, v110
	v_add_f32_e32 v112, v112, v220
	v_mul_f32_e32 v112, 0xbfb8aa3b, v112
	v_exp_f32_e32 v112, v112
	v_add_f32_e32 v110, 1.0, v110
	v_rcp_f32_e32 v114, v110
	v_add_f32_e32 v110, v111, v219
	v_mul_f32_e32 v110, 0xbfb8aa3b, v110
	v_add_f32_e32 v112, 1.0, v112
	v_exp_f32_e32 v110, v110
	v_rcp_f32_e32 v116, v112
	v_add_f32_e32 v112, v113, v221
	v_mul_f32_e32 v112, 0xbfb8aa3b, v112
	v_exp_f32_e32 v112, v112
	v_add_f32_e32 v110, 1.0, v110
	v_pk_mul_f32 v[104:105], v[104:105], v[148:149]
	v_rcp_f32_e32 v115, v110
	v_mul_f32_e32 v118, v104, v96
	v_add_f32_e32 v112, 1.0, v112
	v_fmac_f32_e32 v145, v240, v118
	v_mul_f32_e32 v118, v105, v97
	v_rcp_f32_e32 v117, v112
	v_fmac_f32_e32 v145, v241, v118
	v_pk_add_f32 v[110:111], v[114:115], -1.0 op_sel_hi:[1,0]
	v_pk_add_f32 v[112:113], v[116:117], -1.0 op_sel_hi:[1,0]
	v_pk_fma_f32 v[110:111], v[234:235], v[110:111], 1.0 op_sel_hi:[1,1,0]
	v_and_b32_e32 v91, 0xffff0000, v92
	v_pk_mul_f32 v[110:111], v[110:111], v[158:159]
	s_waitcnt lgkmcnt(1)
	v_pk_mul_f32 v[122:123], v[226:227], v[158:159]
	v_mul_f32_e32 v158, v110, v90
	v_pk_fma_f32 v[112:113], v[236:237], v[112:113], 1.0 op_sel_hi:[1,1,0]
	v_lshlrev_b32_e32 v92, 16, v93
	s_waitcnt lgkmcnt(0)
	v_fmac_f32_e32 v145, v242, v158
	v_mul_f32_e32 v118, v111, v91
	v_pk_mul_f32 v[112:113], v[112:113], v[156:157]
	v_fmac_f32_e32 v145, v243, v118
	v_pk_mul_f32 v[118:119], v[228:229], v[156:157]
	v_mul_f32_e32 v156, v112, v92
	v_fmac_f32_e32 v145, v244, v156
	v_and_b32_e32 v93, 0xffff0000, v93
	v_mul_f32_e32 v120, v113, v93
	v_fmac_f32_e32 v145, v245, v120
	v_pk_mul_f32 v[154:155], v[122:123], v[122:123]
	s_waitcnt lgkmcnt(0)
; __device__ __forceinline__ float sigmoidf_(float x) { return __builtin_amdgcn_rcpf(1.0f + __expf(-x)); }
; __device__ __forceinline__ float allreduce8(float x) { x += dppf(x, 0); x += dppf(x, 1); x += dppf(x, 2); return x; }
; __device__ void rw_scan(const Params& p, int l, unsigned char* shm, int item) {
;     ...
;                     av[e] = sigmoidf_(aa); dec[e] = __expf(-0.6065306597126334f * sigmoidf_(wa)); kkv[e] = ks_[e] * cst[128 + sub * 8 + e]; ssq += kkv[e] * kkv[e];
;                     kd[e] = ks_[e] * (1.0f + (av[e] - 1.0f) * cst[192 + sub * 8 + e]); bpart += rs_[e] * kd[e] * cst[256 + sub * 8 + e]; }
;                 ssq = allreduce8(ssq); bpart = allreduce8(bpart);
;                 const float inrm = __builtin_amdgcn_rcpf(fmaxf(__builtin_amdgcn_sqrtf(ssq), 1e-12f));
; #pragma unroll
;                 for (int hf = 0; hf < 2; ++hf) {
;                     f32x4 o_r, o_w, o_k, o_a, o_b;
; #pragma unroll
;                     for (int e = 0; e < 4; ++e) { const int ee = hf * 4 + e; const float kk = kkv[ee] * inrm; o_r[e] = rs_[ee]; o_w[e] = dec[ee]; o_k[e] = kd[ee]; o_a[e] = -kk; o_b[e] = kk * av[ee]; }
;                     const int o = ptok * 64 + sub * 8 + hf * 4;
;                     *(f32x4*)(sr + o) = o_r; *(f32x4*)(sw + o) = o_w; *(f32x4*)(sk + o) = o_k; *(f32x4*)(sa + o) = o_a; *(f32x4*)(sb + o) = o_b;
;                 }
;                 if ((sub >> 1) == quarter) { const int o = ptok * 16 + (sub & 1) * 8;
;                     *(f32x4*)(sv + o) = (f32x4){vs_[0], vs_[1], vs_[2], vs_[3]}; *(f32x4*)(sv + o + 4) = (f32x4){vs_[4], vs_[5], vs_[6], vs_[7]}; }
;                 if (sub == 0 && quarter == 0) bon[(size_t)(b * T + t) * 12 + h] = bpart;
	v_pk_mul_f32 v[146:147], v[222:223], v[146:147]
	v_pk_mul_f32 v[148:149], v[224:225], v[148:149]
	v_pk_mul_f32 v[156:157], v[146:147], v[146:147]
	v_add_f32_dpp v120, v145, v145 quad_perm:[1,0,3,2] row_mask:0xf bank_mask:0xf bound_ctrl:1
	v_pk_mul_f32 v[158:159], v[148:149], v[148:149]
	v_add_f32_e32 v145, v156, v157
	v_add_f32_e32 v145, v145, v158
	v_add_f32_e32 v145, v145, v159
	v_add_f32_e32 v145, v145, v154
	v_pk_mul_f32 v[124:125], v[118:119], v[118:119]
	v_add_f32_e32 v145, v145, v155
	v_mul_f32_e32 v98, 0xbfb8aa3b, v98
	v_mul_f32_e32 v99, 0xbfb8aa3b, v99
	v_mul_f32_e32 v100, 0xbfb8aa3b, v100
	v_mul_f32_e32 v101, 0xbfb8aa3b, v101
	v_add_f32_e32 v124, v145, v124
	v_exp_f32_e32 v98, v98
	v_exp_f32_e32 v99, v99
	v_exp_f32_e32 v100, v100
	v_exp_f32_e32 v101, v101
	v_mul_f32_e32 v106, 0xbfb8aa3b, v106
	v_mul_f32_e32 v107, 0xbfb8aa3b, v107
	v_mul_f32_e32 v108, 0xbfb8aa3b, v108
	v_mul_f32_e32 v109, 0xbfb8aa3b, v109
	v_add_f32_e32 v124, v124, v125
	v_exp_f32_e32 v106, v106
	v_exp_f32_e32 v107, v107
	v_exp_f32_e32 v108, v108
	v_exp_f32_e32 v109, v109
	v_add_f32_dpp v124, v124, v124 quad_perm:[1,0,3,2] row_mask:0xf bank_mask:0xf bound_ctrl:1
	v_add_f32_e32 v98, 1.0, v98
	v_add_f32_e32 v99, 1.0, v99
	v_add_f32_dpp v124, v124, v124 quad_perm:[2,3,0,1] row_mask:0xf bank_mask:0xf bound_ctrl:1
	v_add_f32_e32 v100, 1.0, v100
	v_add_f32_e32 v101, 1.0, v101
	v_add_f32_dpp v124, v124, v124 row_half_mirror row_mask:0xf bank_mask:0xf bound_ctrl:1
	v_sqrt_f32_e32 v124, v124
	v_rcp_f32_e32 v98, v98
	v_rcp_f32_e32 v99, v99
	v_rcp_f32_e32 v100, v100
	v_rcp_f32_e32 v101, v101
	v_add_f32_e32 v106, 1.0, v106
	v_add_f32_e32 v107, 1.0, v107
	v_add_f32_e32 v108, 1.0, v108
	v_add_f32_e32 v109, 1.0, v109
	v_rcp_f32_e32 v106, v106
	v_rcp_f32_e32 v107, v107
	v_rcp_f32_e32 v108, v108
	v_rcp_f32_e32 v109, v109
	v_max_f32_e32 v124, 0x2b8cbccc, v124
	v_mul_f32_e32 v98, 0xbf1b4598, v98
	v_mul_f32_e32 v99, 0xbf1b4598, v99
	v_mul_f32_e32 v100, 0xbf1b4598, v100
	v_mul_f32_e32 v101, 0xbf1b4598, v101
	v_rcp_f32_e32 v124, v124
	s_bitcmp1_b32 s15, 0
	v_mul_f32_e32 v98, 0x3fb8aa3b, v98
	v_mul_f32_e32 v99, 0x3fb8aa3b, v99
	v_mul_f32_e32 v100, 0x3fb8aa3b, v100
	v_mul_f32_e32 v101, 0x3fb8aa3b, v101
	v_mul_f32_e32 v106, 0xbf1b4598, v106
	v_mul_f32_e32 v107, 0xbf1b4598, v107
	v_mul_f32_e32 v108, 0xbf1b4598, v108
	v_mul_f32_e32 v109, 0xbf1b4598, v109
	s_cselect_b32 s0, 0xa800, 0
	v_exp_f32_e32 v98, v98
	v_exp_f32_e32 v99, v99
	v_exp_f32_e32 v100, v100
	v_exp_f32_e32 v101, v101
	v_mul_f32_e32 v106, 0x3fb8aa3b, v106
	v_mul_f32_e32 v107, 0x3fb8aa3b, v107
	v_mul_f32_e32 v108, 0x3fb8aa3b, v108
	v_mul_f32_e32 v109, 0x3fb8aa3b, v109
	s_add_i32 s8, s0, 0
	v_exp_f32_e32 v106, v106
	v_exp_f32_e32 v107, v107
	v_exp_f32_e32 v108, v108
	v_exp_f32_e32 v109, v109
	v_add_f32_dpp v120, v120, v120 quad_perm:[2,3,0,1] row_mask:0xf bank_mask:0xf bound_ctrl:1
	v_pk_mul_f32 v[154:155], v[146:147], v[124:125] op_sel_hi:[1,0]
	v_pk_mul_f32 v[156:157], v[148:149], v[124:125] op_sel_hi:[1,0]
	v_lshl_add_u32 v125, v182, 2, s8
	v_mov_b32_dpp v121, v120 row_half_mirror row_mask:0xf bank_mask:0xf bound_ctrl:1
	v_xor_b32_e32 v147, 0x80000000, v155
	v_xor_b32_e32 v146, 0x80000000, v154
	v_xor_b32_e32 v148, 0x80000000, v156
	v_xor_b32_e32 v149, 0x80000000, v157
	v_pk_mul_f32 v[150:151], v[150:151], v[154:155]
	v_pk_mul_f32 v[152:153], v[152:153], v[156:157]
	ds_write_b128 v125, v[94:97]
	ds_write_b128 v125, v[98:101] offset:8192
	ds_write_b128 v125, v[102:105] offset:16384
	ds_write_b128 v125, v[146:149] offset:24576
	ds_write_b128 v125, v[150:153] offset:32768
	v_pk_mul_f32 v[98:99], v[122:123], v[124:125] op_sel_hi:[1,0]
	v_pk_mul_f32 v[100:101], v[118:119], v[124:125] op_sel_hi:[1,0]
	v_xor_b32_e32 v95, 0x80000000, v99
	v_xor_b32_e32 v94, 0x80000000, v98
	v_xor_b32_e32 v96, 0x80000000, v100
	v_xor_b32_e32 v97, 0x80000000, v101
	v_pk_mul_f32 v[98:99], v[114:115], v[98:99]
	v_pk_mul_f32 v[100:101], v[116:117], v[100:101]
	ds_write_b128 v125, v[90:93] offset:16
	ds_write_b128 v125, v[106:109] offset:8208
	ds_write_b128 v125, v[110:113] offset:16400
	ds_write_b128 v125, v[94:97] offset:24592
	ds_write_b128 v125, v[98:101] offset:32784
	s_and_saveexec_b64 s[0:1], s[4:5]
	s_cbranch_execz .LBB0_318
	v_lshlrev_b32_e32 v94, 2, v181
	v_lshlrev_b32_e32 v90, 16, v70
	v_and_b32_e32 v91, 0xffff0000, v70
	v_lshlrev_b32_e32 v92, 16, v71
	v_and_b32_e32 v93, 0xffff0000, v71
	v_add3_u32 v94, s8, v180, v94
	v_lshlrev_b32_e32 v70, 16, v72
	v_and_b32_e32 v71, 0xffff0000, v72
	v_lshlrev_b32_e32 v72, 16, v73
	v_and_b32_e32 v73, 0xffff0000, v73
	ds_write_b128 v94, v[90:93] offset:40960
	ds_write_b128 v94, v[70:73] offset:40976

; __device__ __forceinline__ int obid() { int t = blockIdx.x; asm volatile("" : "+s"(t)); return t; }
; __device__ __forceinline__ void na_phase(const Params& p, int l, unsigned char* shm, int item_lo, int item_hi, int wg, int nwg) {
;     ...
;     for (int item = item_lo + wg; item < item_hi; item += nwg) {
;         const int h = item & 7, i = (item >> 3) & 255, b = item >> 11;
;         const int s0 = min(max(i - 4, 0), 248);
;         bf16x8 qf[4][2];
; #pragma unroll
;         for (int mt = 0; mt < 4; ++mt)
; #pragma unroll
;             for (int ks = 0; ks < 2; ++ks) qf[mt][ks] = *(const bf16x8*)(Z + (size_t)(b * T + i * 64 + 16 * mt + n_) * ZLD + ZC_NAQ + h * 64 + 32 * ks + 8 * kg);
; #pragma unroll
;         for (int it = 0; it < 8; ++it) { const int idx = it * NTHR + tid, key = idx >> 3, ch = idx & 7;
;             const size_t tok = (size_t)b * T + (size_t)(s0 + (key >> 6)) * 64 + (key & 63);
;             *(u32x4*)(Ks + key * 144 + ch * 16) = *(const u32x4*)(Z + tok * ZLD + ZC_NAK + h * 64 + ch * 8); }
;         { const size_t tok = (size_t)b * T + (size_t)(s0 + (tid >> 6)) * 64 + (tid & 63);
; #pragma unroll
;           for (int it = 0; it < 8; ++it) { const u32x4 v4 = *(const u32x4*)(Z + tok * ZLD + ZC_NAV + h * 64 + it * 8); const unsigned vv[4] = {v4.x, v4.y, v4.z, v4.w};
; #pragma unroll
;               for (int e = 0; e < 4; ++e) { *(bf16_t*)(Vt + (it * 8 + 2 * e) * 1040 + tid * 2) = (bf16_t)(vv[e] & 0xffffu); *(bf16_t*)(Vt + (it * 8 + 2 * e + 1) * 1040 + tid * 2) = (bf16_t)(vv[e] >> 16); } } }
;         if (lane < 31) brow[w * 32 + lane] = rpb[(size_t)h * 15 * 31 + (size_t)(s0 + w - i + 7) * 31 + lane];
; __global__ void __launch_bounds__(NTHR, 2) mega(Params p) {
;     ...
;         case 1: rw_shift(p, l); __syncthreads(); na_phase(p, l, shm, 0, NA_SPLIT, obid(), (int)gridDim.x); __syncthreads(); ret_states(p, shm); break;
.LBB0_355:
	s_or_b64 exec, exec, s[0:1]
	v_readlane_b32 s23, v253, 0
	s_waitcnt vmcnt(0) lgkmcnt(0)
	s_barrier
	v_mov_b32_e32 v5, v160
	s_cmpk_gt_i32 s23, 0x6ff
	s_cbranch_scc1 .LBB0_505
	v_readlane_b32 s4, v254, 9
	v_ashrrev_i32_e32 v47, 6, v5
	v_and_b32_e32 v2, 48, v5
	v_mov_b32_e32 v3, v1
	v_and_b32_e32 v0, 7, v5
	v_readlane_b32 s6, v254, 11
	v_readlane_b32 s7, v254, 12
	v_readlane_b32 s8, v254, 13
	v_readlane_b32 s9, v254, 14
	v_bfe_u32 v8, v5, 4, 2
	v_lshl_add_u64 v[48:49], s[78:79], 0, v[2:3]
	v_lshlrev_b32_e32 v6, 3, v0
	v_lshl_add_u32 v3, v0, 4, 0
	v_and_b32_e32 v0, 3, v47
	v_and_b32_e32 v53, 15, v5
	v_lshlrev_b32_e32 v12, 2, v8
	v_cmp_ne_u32_e64 s[6:7], 0, v0
	v_cmp_ne_u32_e64 s[8:9], 3, v0
	v_lshlrev_b32_e32 v0, 4, v0
	v_or_b32_e32 v4, v0, v53
	v_or_b32_e32 v57, v0, v12
	v_lshlrev_b32_e32 v0, 1, v53
	v_lshl_add_u64 v[50:51], s[78:79], 0, v[0:1]
	v_add_u32_e32 v0, 0x200, v5
	v_ashrrev_i32_e32 v19, 3, v0
	v_ashrrev_i32_e32 v61, 9, v0
	v_add_u32_e32 v0, 0x400, v5
	v_ashrrev_i32_e32 v20, 3, v0
	v_ashrrev_i32_e32 v63, 9, v0
	v_add_u32_e32 v0, 0x600, v5
	s_mul_i32 s1, s46, 0x3a20
	v_readlane_b32 s10, v254, 15
	v_ashrrev_i32_e32 v21, 3, v0
	v_ashrrev_i32_e32 v65, 9, v0
	v_add_u32_e32 v0, 0x800, v5
	s_mul_hi_i32 s0, s46, 0x3a20
	v_readlane_b32 s11, v254, 16
	s_add_u32 s2, s10, s1
	v_ashrrev_i32_e32 v22, 3, v0
	v_ashrrev_i32_e32 v67, 9, v0
	v_add_u32_e32 v0, 0xa00, v5
	s_addc_u32 s3, s11, s0
	v_ashrrev_i32_e32 v23, 3, v0
	v_ashrrev_i32_e32 v70, 9, v0
	v_add_u32_e32 v0, 0xc00, v5
	v_readlane_b32 s5, v254, 10
	v_readlane_b32 s12, v254, 17
	v_readlane_b32 s13, v254, 18
	v_readlane_b32 s14, v254, 19
	v_readlane_b32 s15, v254, 20
	v_readlane_b32 s16, v254, 21
	v_readlane_b32 s17, v254, 22
	v_readlane_b32 s18, v254, 23
	v_readlane_b32 s19, v254, 24
	v_writelane_b32 v254, s2, 39
	v_and_b32_e32 v46, 63, v5
	v_readlane_b32 s0, v253, 42
	v_lshlrev_b32_e32 v9, 7, v47
	v_ashrrev_i32_e32 v24, 3, v0
	v_ashrrev_i32_e32 v71, 9, v0
	v_add_u32_e32 v0, 0xe00, v5
	v_writelane_b32 v254, s3, 40
	v_lshl_add_u32 v7, v46, 2, s0
	v_lshlrev_b32_e32 v55, 1, v5
	v_cmp_gt_u32_e64 s[2:3], 31, v46
	v_and_b32_e32 v10, 0xfffffcf, v5
	v_add_u32_e32 v13, s0, v9
	v_and_b32_e32 v14, 0xffffffc0, v5
	s_movk_i32 s26, 0x410
	v_ashrrev_i32_e32 v17, 3, v5
	v_ashrrev_i32_e32 v59, 9, v5
	s_movk_i32 s0, 0x90
	v_ashrrev_i32_e32 v25, 3, v0
	v_ashrrev_i32_e32 v72, 9, v0
	v_or_b32_e32 v0, 48, v5
	v_sub_u32_e64 v5, v12, 8 clamp
	v_writelane_b32 v254, s2, 41
	v_mad_u32_u24 v16, v4, s26, 0
	v_and_b32_e32 v4, 0xffffffe0, v17
	v_and_b32_e32 v52, 63, v17
	v_mul_lo_u32 v17, v17, s0
	v_and_b32_e32 v54, 63, v19
	v_mul_lo_u32 v19, v19, s0
	v_and_b32_e32 v56, 63, v20
	v_mul_lo_u32 v20, v20, s0
	v_and_b32_e32 v58, 63, v21
	v_mul_lo_u32 v21, v21, s0
	v_and_b32_e32 v60, 63, v22
	v_mul_lo_u32 v22, v22, s0
	v_and_b32_e32 v62, 63, v23
	v_mul_lo_u32 v23, v23, s0
	v_and_b32_e32 v64, 63, v24
	v_mul_lo_u32 v24, v24, s0
	v_and_b32_e32 v66, 63, v25
	v_mul_lo_u32 v25, v25, s0
	v_mul_lo_u32 v10, v10, s0
	v_mul_lo_u32 v26, v0, s0
	v_cmp_ge_u32_e64 s[0:1], v53, v5
	v_sub_u32_e32 v5, v53, v12
	v_writelane_b32 v254, s3, 42
	v_lshl_add_u32 v74, v5, 2, v13
	v_or_b32_e32 v5, 1, v12
	v_writelane_b32 v254, s0, 43
	v_sub_u32_e64 v27, v5, 8 clamp
	v_mul_u32_u24_e32 v75, 0x1040, v8
	v_writelane_b32 v254, s1, 44
	v_max_u32_e32 v8, 8, v5
	v_cmp_ge_u32_e64 s[0:1], v53, v27
	v_sub_u32_e32 v27, v53, v5
	v_mul_u32_u24_e32 v77, 0x410, v5
	v_or_b32_e32 v5, 2, v12
	v_writelane_b32 v254, s0, 45
	v_lshl_add_u32 v76, v27, 2, v13
	v_max_u32_e32 v27, 8, v5
	v_sub_u32_e64 v28, v5, 8 clamp
	v_sub_u32_e32 v5, v53, v5
	v_writelane_b32 v254, s1, 46
	v_cmp_ge_u32_e64 s[0:1], v53, v28
	v_lshl_add_u32 v78, v5, 2, v13
	v_or_b32_e32 v5, 3, v12
	v_and_b32_e32 v0, 0xffffff9e, v55
	v_writelane_b32 v254, s0, 47
	v_sub_u32_e64 v29, v5, 8 clamp
	v_add_u32_e32 v73, 0, v0
	v_max_u32_e32 v0, 8, v12
	v_writelane_b32 v254, s1, 48
	v_max_u32_e32 v28, 8, v5
	v_cmp_ge_u32_e64 s[0:1], v53, v29
	v_sub_u32_e32 v5, v53, v5
	v_add_u32_e32 v0, 8, v0
	v_writelane_b32 v254, s0, 49
	v_lshl_add_u32 v79, v5, 2, v13
	v_or_b32_e32 v5, 16, v53
	v_writelane_b32 v254, s1, 50
	v_cmp_lt_u32_e64 s[0:1], v5, v0
	v_add_u32_e32 v8, 8, v8
	v_add_u32_e32 v27, 8, v27
	v_writelane_b32 v254, s0, 51
	v_add_u32_e32 v28, 8, v28
	v_or_b32_e32 v29, v5, v14
	v_writelane_b32 v254, s1, 52
	v_cmp_lt_u32_e64 s[0:1], v5, v8
	v_or_b32_e32 v8, 32, v53
	v_or_b32_e32 v0, v8, v14
	v_writelane_b32 v254, s0, 53
	v_lshl_add_u32 v81, v0, 1, 0
	v_readlane_b32 s25, v253, 43
	v_writelane_b32 v254, s1, 54
	v_cmp_lt_u32_e64 s[0:1], v5, v27
	v_or_b32_e32 v27, 48, v53
	v_or_b32_e32 v0, v27, v14
	v_writelane_b32 v254, s0, 55
	v_lshl_add_u32 v82, v0, 1, 0
	v_or_b32_e32 v0, 16, v12
	v_lshl_add_u32 v80, v29, 1, 0
	v_writelane_b32 v254, s1, 56
	v_cmp_lt_u32_e64 s[0:1], v5, v28
	v_sub_u32_e32 v29, v53, v0
	v_mul_u32_u24_e32 v84, 0x410, v0
	v_or_b32_e32 v0, 17, v12
	v_lshl_add_u32 v15, v14, 2, s25
	v_writelane_b32 v254, s0, 57
	v_add_u32_e32 v14, 8, v12
	v_sub_u32_e32 v0, v53, v0
	v_writelane_b32 v254, s1, 58
	v_cmp_ge_u32_e64 s[0:1], v53, v14
	v_lshl_add_u32 v85, v0, 2, v13
	v_or_b32_e32 v0, 18, v12
	v_writelane_b32 v254, s0, 59
	v_lshl_add_u32 v83, v29, 2, v13
	v_add_u32_e32 v29, 9, v12
	v_sub_u32_e32 v0, v53, v0
	v_writelane_b32 v254, s1, 60
	v_cmp_ge_u32_e64 s[0:1], v53, v29
	v_lshl_add_u32 v86, v0, 2, v13
	v_or_b32_e32 v0, 19, v12
	v_add_u32_e32 v28, 24, v12
	v_writelane_b32 v254, s0, 61
	v_sub_u32_e32 v0, v53, v0
	v_add_u32_e32 v30, 25, v12
	v_writelane_b32 v254, s1, 62
	v_lshl_add_u32 v87, v0, 2, v13
	v_cmp_ge_u32_e32 vcc, v5, v14
	v_cmp_lt_u32_e64 s[0:1], v5, v28
	v_or_b32_e32 v0, 32, v12
	v_add_u32_e32 v31, 10, v12
; __device__ __forceinline__ float bf2f(bf16_t b) { return __uint_as_float(((unsigned)b) << 16); }
; __device__ __forceinline__ bf16_t f2bf(float f) { return (bf16_t)(cvt_pk_bf16(f, 0.f) & 0xffffu); }
; __device__ __forceinline__ float allreduce16(float x) { x += dppf(x, 0); x += dppf(x, 1); x += dppf(x, 2); x += dppf(x, 3); return x; }
; __device__ __forceinline__ void na_phase(const Params& p, int l, unsigned char* shm, int item_lo, int item_hi, int wg, int nwg) {
;     ...
;         for (int mt = 0; mt < 4; ++mt) {
;             float rs[4] = {0.f, 0.f, 0.f, 0.f};
; #pragma unroll
;             for (int nt = 0; nt < 4; ++nt)
; #pragma unroll
;                 for (int i2 = 0; i2 < 4; ++i2) { const int q = 16 * mt + 4 * kg + i2, col = 16 * nt + n_, cs = min(max(q - 8, 0), 48); const bool ok = (col >= cs) && (col < cs + 16);
;                     const float s = acc[mt][nt][i2] * 0.125f + brow[w * 32 + (ok ? col - q + 15 : 0)];
;                     const bf16_t pb = f2bf(ok ? __expf(fminf(s, 60.0f)) : 0.0f);
;                     rs[i2] += bf2f(pb);
;                     *(bf16_t*)(Ks + q * 1040 + (w * 64 + col) * 2) = pb; }
; #pragma unroll
;             for (int i2 = 0; i2 < 4; ++i2) { const float t_ = allreduce16(rs[i2]); if (n_ == 0) red[w * 64 + 16 * mt + 4 * kg + i2] = t_; }
	s_and_b64 s[2:3], vcc, s[0:1]
	v_cmp_ge_u32_e32 vcc, v5, v29
	v_cmp_lt_u32_e64 s[0:1], v5, v30
	v_mul_u32_u24_e32 v88, 0x410, v0
	v_or_b32_e32 v14, 33, v12
	v_sub_u32_e32 v0, v53, v0
	v_cmp_ge_u32_e64 s[30:31], v53, v31
	v_add_u32_e32 v32, 26, v12
	s_and_b64 s[10:11], vcc, s[0:1]
	v_cmp_ge_u32_e32 vcc, v5, v31
	v_or_b32_e32 v31, 34, v12
	v_lshl_add_u32 v89, v0, 2, v13
	v_sub_u32_e32 v0, v53, v14
	v_add_u32_e32 v33, 11, v12
	v_add_u32_e32 v34, 27, v12
	v_cmp_lt_u32_e64 s[0:1], v5, v32
	v_or_b32_e32 v35, 35, v12
	v_lshl_add_u32 v90, v0, 2, v13
	v_sub_u32_e32 v0, v53, v31
	v_cmp_ge_u32_e64 s[36:37], v5, v28
	v_cmp_ge_u32_e64 s[38:39], v5, v30
	v_cmp_ge_u32_e64 s[40:41], v5, v32
	s_and_b64 s[12:13], vcc, s[0:1]
	v_cmp_ge_u32_e32 vcc, v5, v33
	v_cmp_ge_u32_e64 s[42:43], v5, v34
	v_cmp_lt_u32_e64 s[0:1], v5, v34
	v_add_u32_e32 v5, 40, v12
	v_lshl_add_u32 v91, v0, 2, v13
	v_sub_u32_e32 v0, v53, v35
	s_and_b64 s[14:15], vcc, s[0:1]
	v_add_u32_e32 v29, 41, v12
	v_lshl_add_u32 v92, v0, 2, v13
	v_cmp_ge_u32_e32 vcc, v8, v28
	v_cmp_lt_u32_e64 s[0:1], v8, v5
	v_cmp_lt_u32_e64 s[52:53], v27, v5
	v_or_b32_e32 v0, 48, v12
	v_min_u32_e32 v5, 8, v12
	v_cmp_ge_u32_e64 s[34:35], v53, v33
	v_cmp_lt_u32_e64 s[44:45], v8, v28
	v_add_u32_e32 v33, 42, v12
	s_and_b64 s[16:17], vcc, s[0:1]
	v_cmp_ge_u32_e32 vcc, v8, v30
	v_cmp_lt_u32_e64 s[0:1], v8, v29
	v_add_u32_e32 v14, 40, v5
	v_add_u32_e32 v28, 56, v5
	v_mul_u32_u24_e32 v93, 0x410, v0
	v_or_b32_e32 v5, 49, v12
	v_sub_u32_e32 v0, v53, v0
	s_and_b64 s[18:19], vcc, s[0:1]
	v_cmp_ge_u32_e32 vcc, v8, v32
	v_cmp_lt_u32_e64 s[0:1], v8, v33
	v_or_b32_e32 v31, 50, v12
	v_lshl_add_u32 v94, v0, 2, v13
	v_sub_u32_e32 v0, v53, v5
	v_or_b32_e32 v18, v4, v53
	v_cmp_lt_u32_e64 s[50:51], v8, v34
	s_and_b64 s[20:21], vcc, s[0:1]
	v_cmp_ge_u32_e32 vcc, v8, v34
	v_or_b32_e32 v34, 51, v12
	v_lshl_add_u32 v95, v0, 2, v13
	v_sub_u32_e32 v0, v53, v31
	v_cmp_lt_u32_e64 s[48:49], v8, v32
	v_add_u32_e32 v36, 43, v12
	v_cmp_lt_u32_e64 s[54:55], v27, v29
	v_min_u32_e32 v29, 7, v12
	v_min_u32_e32 v32, 6, v12
	v_min_u32_e32 v12, 5, v12
	v_lshl_add_u32 v96, v0, 2, v13
	v_sub_u32_e32 v0, v53, v34
	s_add_i32 s24, 0, 0x12000
	v_mul_lo_u32 v18, v18, s26
	v_add_u32_e32 v11, 0, v2
	v_cmp_lt_u32_e64 s[46:47], v8, v30
	v_cmp_lt_u32_e64 s[0:1], v8, v36
	v_cmp_lt_u32_e64 s[56:57], v27, v33
	v_add_u32_e32 v30, 41, v29
	v_add_u32_e32 v29, 57, v29
	v_add_u32_e32 v33, 42, v32
	v_add_u32_e32 v32, 58, v32
	v_add_u32_e32 v35, 43, v12
	v_add_u32_e32 v12, 59, v12
	v_lshl_add_u32 v97, v0, 2, v13
	v_add_u32_e32 v13, s24, v2
	v_or_b32_e32 v31, 64, v2
	v_add_u32_e32 v34, s24, v18
	v_or_b32_e32 v37, 0x80, v2
	v_or_b32_e32 v38, 0xc0, v2
	v_or_b32_e32 v39, 0x100, v2
	v_or_b32_e32 v40, 0x140, v2
	v_or_b32_e32 v41, 0x180, v2
	v_or_b32_e32 v42, 0x1c0, v2
	v_or_b32_e32 v43, 0x200, v2
	v_or_b32_e32 v44, 0x240, v2
	v_or_b32_e32 v45, 0x280, v2
	v_or_b32_e32 v68, 0x2c0, v2
	v_or_b32_e32 v69, 0x300, v2
	v_or_b32_e32 v129, 0x340, v2
	v_or_b32_e32 v142, 0x380, v2
	v_or_b32_e32 v143, 0x3c0, v2
	v_ashrrev_i32_e32 v5, 31, v4
	v_or_b32_e32 v99, 1, v57
	v_or_b32_e32 v101, 2, v57
	v_or_b32_e32 v103, 3, v57
	v_cmp_eq_u32_e64 s[4:5], 0, v53
	s_and_b64 s[0:1], vcc, s[0:1]
	v_lshl_add_u32 v98, v57, 2, s25
	v_lshl_add_u32 v100, v99, 2, s25
	v_lshl_add_u32 v102, v101, 2, s25
	v_lshl_add_u32 v104, v103, 2, s25
	v_lshlrev_b32_e32 v0, 1, v6
	v_add_u32_e32 v105, v3, v17
	v_add_u32_e32 v106, v3, v19
	v_add_u32_e32 v107, v3, v20
	v_add_u32_e32 v108, v3, v21
	v_add_u32_e32 v109, v3, v22
	v_add_u32_e32 v110, v3, v23
	v_add_u32_e32 v111, v3, v24
	v_add_u32_e32 v112, v3, v25
	v_add_u32_e32 v113, v7, v9
	v_add_u32_e32 v114, v11, v10
	v_add_u32_e32 v115, v11, v26
	v_add_u32_e32 v116, v13, v18
	v_add_u32_e32 v117, v34, v31
	v_add_u32_e32 v118, v34, v37
	v_add_u32_e32 v119, v34, v38
	v_add_u32_e32 v120, v34, v39
	v_add_u32_e32 v121, v34, v40
	v_add_u32_e32 v122, v34, v41
	v_add_u32_e32 v123, v34, v42
	v_add_u32_e32 v124, v34, v43
	v_add_u32_e32 v125, v34, v44
	v_add_u32_e32 v126, v34, v45
	v_add_u32_e32 v127, v34, v68
	v_add_u32_e32 v128, v34, v69
	v_add_u32_e32 v129, v34, v129
	v_add_u32_e32 v142, v34, v142
	v_add_u32_e32 v143, v34, v143
	v_lshlrev_b64 v[68:69], 1, v[4:5]
	v_add_u32_e32 v144, v15, v2
	v_add_u32_e32 v145, v16, v2
	v_cmp_lt_u32_e64 s[58:59], v27, v36
	v_cmp_ge_u32_e64 s[60:61], v8, v14
	v_cmp_ge_u32_e64 s[62:63], v8, v30
	v_cmp_ge_u32_e64 s[64:65], v8, v33
	v_cmp_ge_u32_e64 s[66:67], v8, v35
	v_cmp_lt_u32_e64 s[68:69], v27, v28
	v_cmp_lt_u32_e64 s[70:71], v27, v29
	v_cmp_lt_u32_e64 s[72:73], v27, v32
	v_cmp_lt_u32_e64 s[74:75], v27, v12
	s_branch .LBB0_358
; __device__ __forceinline__ bf16_t f2bf(float f) { return (bf16_t)(cvt_pk_bf16(f, 0.f) & 0xffffu); }
; __device__ __forceinline__ void na_phase(const Params& p, int l, unsigned char* shm, int item_lo, int item_hi, int wg, int nwg) {
;     ...
; #pragma unroll
;             for (int i2 = 0; i2 < 4; ++i2) { const int q = 16 * qt + 4 * kg + i2; float tot = 0.f;
; #pragma unroll
;                 for (int ww = 0; ww < 8; ++ww) tot += red[ww * 64 + q];
;                 const float inv = 1.0f / tot;
; #pragma unroll
;                 for (int j = 0; j < 2; ++j) Z[(size_t)(b * T + i * 64 + q) * ZLD + ZC_NAQ + h * 64 + 16 * (2 * dp + j) + n_] = f2bf(o2[j][i2] * inv); }
;         }
;         __syncthreads();
.LBB0_357:
	s_or_b64 exec, exec, vcc
	ds_read2st64_b32 v[12:13], v98 offset1:1
	s_lshl_b32 s25, s25, 6
	s_lshl_b32 s76, s25, 1
	v_lshl_add_u64 v[10:11], v[50:51], 0, s[76:77]
	s_add_i32 s23, s23, s28
	s_waitcnt lgkmcnt(0)
	v_add_f32_e32 v12, 0, v12
	v_add_f32_e32 v14, v12, v13
	ds_read2st64_b32 v[12:13], v98 offset0:2 offset1:3
	s_cmpk_lt_i32 s23, 0x700
	s_waitcnt lgkmcnt(0)
	v_add_f32_e32 v12, v14, v12
	v_add_f32_e32 v14, v12, v13
	ds_read2st64_b32 v[12:13], v98 offset0:4 offset1:5
	s_waitcnt lgkmcnt(0)
	v_add_f32_e32 v12, v14, v12
	v_add_f32_e32 v14, v12, v13
	ds_read2st64_b32 v[12:13], v98 offset0:6 offset1:7
	s_waitcnt lgkmcnt(0)
	v_add_f32_e32 v12, v14, v12
	v_add_f32_e32 v12, v12, v13
	v_div_scale_f32 v13, s[26:27], v12, v12, 1.0
	v_rcp_f32_e32 v14, v13
	s_nop 0
	v_fma_f32 v15, -v13, v14, 1.0
	v_fmac_f32_e32 v14, v15, v14
	v_div_scale_f32 v15, vcc, 1.0, v12, 1.0
	v_mul_f32_e32 v16, v15, v14
	v_fma_f32 v17, -v13, v16, v15
	v_fmac_f32_e32 v16, v17, v14
	v_fma_f32 v13, -v13, v16, v15
	v_div_fmas_f32 v13, v13, v14, v16
	v_div_fixup_f32 v14, v13, v12, 1.0
	v_or_b32_e32 v12, s24, v57
	v_mad_i64_i32 v[12:13], s[26:27], v12, s22, v[10:11]
	v_mul_f32_e32 v6, v6, v14
	v_lshl_add_u64 v[12:13], v[12:13], 0, v[68:69]
	v_mul_f32_e32 v2, v2, v14
	v_cvt_pk_bf16_f32 v6, v6, v1
	global_store_short v[12:13], v6, off
	v_cvt_pk_bf16_f32 v2, v2, v1
	global_store_short v[12:13], v2, off offset:32
	ds_read2st64_b32 v[12:13], v100 offset1:1
	s_waitcnt lgkmcnt(0)
	v_add_f32_e32 v2, 0, v12
	v_add_f32_e32 v2, v2, v13
	ds_read2st64_b32 v[12:13], v100 offset0:2 offset1:3
	s_waitcnt lgkmcnt(0)
	v_add_f32_e32 v2, v2, v12
	v_add_f32_e32 v2, v2, v13
	ds_read2st64_b32 v[12:13], v100 offset0:4 offset1:5
	s_waitcnt lgkmcnt(0)
	v_add_f32_e32 v2, v2, v12
	v_add_f32_e32 v2, v2, v13
	ds_read2st64_b32 v[12:13], v100 offset0:6 offset1:7
	s_waitcnt lgkmcnt(0)
	v_add_f32_e32 v2, v2, v12
	v_add_f32_e32 v2, v2, v13
	v_div_scale_f32 v6, s[26:27], v2, v2, 1.0
	v_rcp_f32_e32 v12, v6
	s_nop 0
	v_fma_f32 v13, -v6, v12, 1.0
	v_fmac_f32_e32 v12, v13, v12
	v_div_scale_f32 v13, vcc, 1.0, v2, 1.0
	v_mul_f32_e32 v14, v13, v12
	v_fma_f32 v15, -v6, v14, v13
	v_fmac_f32_e32 v14, v15, v12
	v_fma_f32 v6, -v6, v14, v13
	v_div_fmas_f32 v6, v6, v12, v14
	v_div_fixup_f32 v2, v6, v2, 1.0
	v_or_b32_e32 v6, s24, v99
	v_mad_i64_i32 v[12:13], s[26:27], v6, s22, v[10:11]
	v_mul_f32_e32 v6, v7, v2
	v_mul_f32_e32 v2, v3, v2
	v_cvt_pk_bf16_f32 v14, v6, v1
	v_lshl_add_u64 v[6:7], v[12:13], 0, v[68:69]
	v_cvt_pk_bf16_f32 v2, v2, v1
	global_store_short v[6:7], v2, off offset:32
	ds_read2st64_b32 v[2:3], v102 offset1:1
	global_store_short v[6:7], v14, off
	s_waitcnt lgkmcnt(0)
	v_add_f32_e32 v2, 0, v2
	v_add_f32_e32 v6, v2, v3
	ds_read2st64_b32 v[2:3], v102 offset0:2 offset1:3
	s_waitcnt lgkmcnt(0)
	v_add_f32_e32 v2, v6, v2
	v_add_f32_e32 v6, v2, v3
	ds_read2st64_b32 v[2:3], v102 offset0:4 offset1:5
	s_waitcnt lgkmcnt(0)
	v_add_f32_e32 v2, v6, v2
	v_add_f32_e32 v6, v2, v3
	ds_read2st64_b32 v[2:3], v102 offset0:6 offset1:7
	s_waitcnt lgkmcnt(0)
	v_add_f32_e32 v2, v6, v2
	v_add_f32_e32 v2, v2, v3
	v_div_scale_f32 v3, s[26:27], v2, v2, 1.0
	v_rcp_f32_e32 v6, v3
	s_nop 0
	v_fma_f32 v7, -v3, v6, 1.0
	v_fmac_f32_e32 v6, v7, v6
	v_div_scale_f32 v7, vcc, 1.0, v2, 1.0
	v_mul_f32_e32 v12, v7, v6
	v_fma_f32 v13, -v3, v12, v7
	v_fmac_f32_e32 v12, v13, v6
	v_fma_f32 v3, -v3, v12, v7
	v_div_fmas_f32 v3, v3, v6, v12
	v_div_fixup_f32 v6, v3, v2, 1.0
	v_or_b32_e32 v2, s24, v101
	v_mad_i64_i32 v[2:3], s[26:27], v2, s22, v[10:11]
	v_mul_f32_e32 v7, v8, v6
	v_lshl_add_u64 v[2:3], v[2:3], 0, v[68:69]
	v_mul_f32_e32 v4, v4, v6
	v_cvt_pk_bf16_f32 v7, v7, v1
	global_store_short v[2:3], v7, off
	v_cvt_pk_bf16_f32 v4, v4, v1
	global_store_short v[2:3], v4, off offset:32
	ds_read2st64_b32 v[2:3], v104 offset1:1
	s_waitcnt lgkmcnt(0)
	v_add_f32_e32 v2, 0, v2
	v_add_f32_e32 v4, v2, v3
	ds_read2st64_b32 v[2:3], v104 offset0:2 offset1:3
	s_waitcnt lgkmcnt(0)
	v_add_f32_e32 v2, v4, v2
	v_add_f32_e32 v4, v2, v3
	ds_read2st64_b32 v[2:3], v104 offset0:4 offset1:5
	s_waitcnt lgkmcnt(0)
	v_add_f32_e32 v2, v4, v2
	v_add_f32_e32 v4, v2, v3
	ds_read2st64_b32 v[2:3], v104 offset0:6 offset1:7
	s_waitcnt lgkmcnt(0)
	v_add_f32_e32 v2, v4, v2
	v_add_f32_e32 v2, v2, v3
	v_div_scale_f32 v3, s[26:27], v2, v2, 1.0
	v_rcp_f32_e32 v4, v3
	s_nop 0
	v_fma_f32 v6, -v3, v4, 1.0
	v_fmac_f32_e32 v4, v6, v4
	v_div_scale_f32 v6, vcc, 1.0, v2, 1.0
	v_mul_f32_e32 v7, v6, v4
	v_fma_f32 v8, -v3, v7, v6
	v_fmac_f32_e32 v7, v8, v4
	v_fma_f32 v3, -v3, v7, v6
	v_div_fmas_f32 v3, v3, v4, v7
	v_div_fixup_f32 v4, v3, v2, 1.0
	v_or_b32_e32 v2, s24, v103
	v_mad_i64_i32 v[2:3], s[24:25], v2, s22, v[10:11]
	v_mul_f32_e32 v6, v9, v4
	v_lshl_add_u64 v[2:3], v[2:3], 0, v[68:69]
	v_mul_f32_e32 v4, v5, v4
	v_cvt_pk_bf16_f32 v6, v6, v1
	global_store_short v[2:3], v6, off
	v_cvt_pk_bf16_f32 v4, v4, v1
	global_store_short v[2:3], v4, off offset:32
	s_barrier
	s_cbranch_scc0 .LBB0_504
